# P1 tile order: per-step workgroup rotation re-chosen from instruction-count estimates of each epilogue kind (rotations 0 0 12 0 0 20 28 28)
# baseline (speedup 1.0000x reference)
.LBB0_90:
	s_bfe_u32 s2, s74, 0x20001
	s_mulk_i32 s2, 0x44
	s_lshl_b32 s3, s72, 1
	s_add_i32 s2, s2, s3
	s_and_b32 s3, s74, 1
	s_add_i32 s2, s2, s3
	s_lshr_b32 s3, s2, 5
	s_mov_b32 s12, 0x3000
	s_mov_b32 s13, 0xe7280
	s_cmp_gt_u32 s3, 3
	s_cselect_b32 s12, s13, s12
	s_and_b32 s3, s3, 3
	s_mul_i32 s3, s3, 5
	s_lshr_b32 s12, s12, s3
	s_and_b32 s12, s12, 31
	s_add_i32 s12, s2, s12
	s_and_b32 s12, s12, 31
	s_and_b32 s3, s2, -32
	s_or_b32 s12, s12, s3
	s_cmp_lt_u32 s2, 0x100
	s_cselect_b32 s2, s12, s2
	s_and_b32 s74, s74, -8
	s_mul_i32 s3, s2, 0xf1
	s_lshr_b32 s3, s3, 14
	s_lshl_b32 s72, s3, 1
	s_add_i32 s74, s74, s72
	s_mulk_i32 s3, 0x44
	s_sub_i32 s2, s2, s3
	s_lshr_b32 s72, s2, 1
	s_and_b32 s2, s2, 1
	s_add_i32 s74, s74, s2
	s_add_u32 s2, s80, 0x2000000
	s_addc_u32 s3, s81, 0
	v_writelane_b32 v254, s2, 20
	v_lshrrev_b32_e32 v246, 1, v0
	v_lshrrev_b32_e32 v239, 6, v0
	v_writelane_b32 v254, s3, 21
	v_writelane_b32 v254, s65, 22
	v_writelane_b32 v254, s63, 23
	v_writelane_b32 v254, s60, 24
	v_and_b32_e32 v2, 32, v0
	v_bfe_u32 v199, v0, 2, 4
	v_writelane_b32 v254, s61, 25
	v_writelane_b32 v254, s66, 26
	v_and_b32_e32 v203, 24, v246
	v_bfe_u32 v228, v0, 2, 2
	v_writelane_b32 v254, s67, 27
	v_writelane_b32 v254, s62, 28
	v_writelane_b32 v254, s56, 29
	v_lshlrev_b32_e32 v3, 3, v239
	v_lshrrev_b32_e32 v245, 5, v0
	v_or_b32_e32 v233, 0x2000, v230
	s_andn2_b64 vcc, exec, s[0:1]
	v_writelane_b32 v254, s57, 30
	s_mov_b32 s0, s58
	v_bitop3_b32 v232, v230, v2, 48 bitop3:0x6c
	v_or_b32_e32 v2, v203, v228
	v_and_or_b32 v229, v3, 48, v199
	v_or_b32_e32 v3, v245, v3
	v_lshrrev_b32_e32 v242, 10, v233
	v_writelane_b32 v254, s0, 31
	v_and_or_b32 v240, v3, 36, v2
	v_lshlrev_b32_e32 v3, 3, v242
	s_movk_i32 s2, 0x70
	v_writelane_b32 v254, s1, 32
	v_and_or_b32 v243, v3, s2, v199
	v_or_b32_e32 v3, v3, v245
	s_movk_i32 s2, 0x64
	v_writelane_b32 v254, s64, 33
	v_and_or_b32 v241, v3, s2, v2
	v_bfe_u32 v226, v0, 4, 2
	v_lshlrev_b32_e32 v2, 6, v0
	v_writelane_b32 v254, s54, 34
	v_lshlrev_b32_e32 v227, 4, v226
	v_and_b32_e32 v235, 0x3c0, v2
	v_and_b32_e32 v236, 32, v198
	v_writelane_b32 v254, s52, 35
	v_lshlrev_b32_e32 v237, 11, v229
	v_lshlrev_b32_e32 v238, 11, v243
	v_and_b32_e32 v231, 15, v0
	v_bitop3_b32 v201, v227, v236, v235 bitop3:0x36
	v_and_b32_e32 v234, 64, v0
	v_writelane_b32 v254, s53, 36
	s_cbranch_vccnz .LBB0_171
	s_lshr_b32 s2, s14, 6
	s_ashr_i32 s75, s74, 31
	s_lshr_b32 s6, s14, 8
	s_lshl_b32 s3, s2, 10
	s_lshl_b64 s[8:9], s[74:75], 19
	s_cmp_gt_i32 s33, 0
	s_cselect_b32 s5, 0x40000, 0
	s_ashr_i32 s73, s72, 31
	s_lshl_b64 s[0:1], s[72:73], 19
	s_add_u32 s0, s10, s0
	s_addc_u32 s1, s11, s1
	s_add_i32 s61, s3, 0
	v_or_b32_e32 v2, v232, v234
	s_add_i32 s73, s61, 0x10000
	s_add_i32 s75, s61, 0x12000
	v_or_b32_e32 v206, v237, v2
	v_lshl_or_b32 v208, v240, 11, v2
	v_lshlrev_b32_e32 v2, 6, v242
	s_add_u32 s3, s80, s8
	v_and_b32_e32 v3, 64, v2
	s_addc_u32 s7, s81, s9
	v_or_b32_e32 v2, v3, v232
	s_mov_b32 m0, s73
	s_add_u32 s8, s0, 0x40000
	v_lshl_or_b32 v212, v241, 11, v2
	global_load_lds_dwordx4 v208, s[0:1]
	s_mov_b32 m0, s75
	s_addc_u32 s9, s1, 0
	s_add_i32 s92, s61, 0x14000
	s_add_i32 s93, s61, 0x16000
	global_load_lds_dwordx4 v212, s[0:1]
	s_mov_b32 m0, s92
	s_add_u32 s76, s3, s5
	global_load_lds_dwordx4 v208, s[8:9]
	s_mov_b32 m0, s93
	s_addc_u32 s77, s7, 0
	s_add_i32 s94, s61, 0x2000
	global_load_lds_dwordx4 v212, s[8:9]
	s_mov_b32 m0, s61
	s_add_u32 s8, s76, 0x40000
	v_or_b32_e32 v210, v238, v2
	global_load_lds_dwordx4 v206, s[76:77]
	s_mov_b32 m0, s94
	s_addc_u32 s9, s77, 0
	s_add_i32 s95, s61, 0x4000
	global_load_lds_dwordx4 v210, s[76:77]
	s_mov_b32 m0, s95
	s_add_i32 s96, s61, 0x6000
	global_load_lds_dwordx4 v206, s[8:9]
	s_mov_b32 m0, s96
	v_mov_b32_e32 v2, 0
	global_load_lds_dwordx4 v210, s[8:9]
	v_mov_b32_e32 v209, v2
	v_mov_b32_e32 v213, v2
	v_mov_b32_e32 v207, v2
	v_mov_b32_e32 v211, v2
	s_cmp_eq_u32 s6, 1
	s_mov_b32 s5, 0
	s_mov_b32 s48, 0x10000
	v_lshl_add_u64 v[8:9], s[0:1], 0, v[208:209]
	v_lshl_add_u64 v[6:7], s[0:1], 0, v[212:213]
	v_lshl_add_u64 v[10:11], s[76:77], 0, v[206:207]
	v_lshl_add_u64 v[4:5], s[76:77], 0, v[210:211]
	s_cselect_b64 s[8:9], -1, 0
	s_cmp_lg_u32 s6, 1
	s_cbranch_scc1 .LBB0_93
	s_barrier

.LBB0_104:
	s_bfe_u32 s2, s64, 0x20001
	s_mulk_i32 s2, 0x44
	s_lshl_b32 s3, s62, 1
	s_add_i32 s2, s2, s3
	s_and_b32 s3, s64, 1
	s_add_i32 s2, s2, s3
	s_lshr_b32 s3, s2, 5
	s_mov_b32 s12, 0x3000
	s_mov_b32 s13, 0xe7280
	s_cmp_gt_u32 s3, 3
	s_cselect_b32 s12, s13, s12
	s_and_b32 s3, s3, 3
	s_mul_i32 s3, s3, 5
	s_lshr_b32 s12, s12, s3
	s_and_b32 s12, s12, 31
	s_add_i32 s12, s2, s12
	s_and_b32 s12, s12, 31
	s_and_b32 s3, s2, -32
	s_or_b32 s12, s12, s3
	s_cmp_lt_u32 s2, 0x100
	s_cselect_b32 s2, s12, s2
	s_and_b32 s64, s64, -8
	s_mul_i32 s3, s2, 0xf1
	s_lshr_b32 s3, s3, 14
	s_lshl_b32 s62, s3, 1
	s_add_i32 s64, s64, s62
	s_mulk_i32 s3, 0x44
	s_sub_i32 s2, s2, s3
	s_lshr_b32 s62, s2, 1
	s_and_b32 s2, s2, 1
	s_add_i32 s64, s64, s2
	s_ashr_i32 s65, s64, 31
	s_lshl_b64 s[2:3], s[64:65], 19
	s_add_u32 s2, s80, s2
	s_addc_u32 s3, s81, s3
	s_cmp_gt_i32 s42, 0
	s_cselect_b32 s4, 0x40000, 0
	s_add_u32 s68, s2, s4
	s_addc_u32 s69, s3, 0
	s_and_b64 s[2:3], s[66:67], exec
	s_cselect_b32 s4, s69, s77
	s_cselect_b32 s43, s68, s76
	s_ashr_i32 s63, s62, 31
	s_lshl_b64 s[2:3], s[62:63], 19
	s_add_u32 s70, s10, s2
	s_addc_u32 s71, s11, s3
	s_and_b64 s[2:3], s[66:67], exec
	s_cselect_b32 s63, s71, s1
	s_cselect_b32 s65, s70, s0
	s_cmp_lt_i32 s33, 0
	v_mov_b32_e32 v4, v2
	v_mov_b32_e32 v5, v2
	s_cselect_b64 s[86:87], -1, 0
	s_add_u32 s36, s0, 0x100
	v_mov_b32_e32 v3, v2
	v_mov_b64_e32 v[70:71], v[4:5]
	v_mov_b64_e32 v[72:73], v[4:5]
	v_mov_b64_e32 v[74:75], v[4:5]
	v_mov_b64_e32 v[76:77], v[4:5]
	v_mov_b64_e32 v[78:79], v[4:5]
	v_mov_b64_e32 v[80:81], v[4:5]
	v_mov_b64_e32 v[82:83], v[4:5]
	v_mov_b64_e32 v[84:85], v[4:5]
	v_mov_b64_e32 v[86:87], v[4:5]
	v_mov_b64_e32 v[88:89], v[4:5]
	v_mov_b64_e32 v[90:91], v[4:5]
	v_mov_b64_e32 v[92:93], v[4:5]
	v_mov_b64_e32 v[94:95], v[4:5]
	v_mov_b64_e32 v[96:97], v[4:5]
	v_mov_b64_e32 v[98:99], v[4:5]
	v_mov_b64_e32 v[100:101], v[4:5]
	v_mov_b64_e32 v[102:103], v[4:5]
	v_mov_b64_e32 v[104:105], v[4:5]
	v_mov_b64_e32 v[106:107], v[4:5]
	v_mov_b64_e32 v[108:109], v[4:5]
	v_mov_b64_e32 v[110:111], v[4:5]
	v_mov_b64_e32 v[112:113], v[4:5]
	v_mov_b64_e32 v[114:115], v[4:5]
	v_mov_b64_e32 v[116:117], v[4:5]
	v_mov_b64_e32 v[118:119], v[4:5]
	v_mov_b64_e32 v[120:121], v[4:5]
	v_mov_b64_e32 v[122:123], v[4:5]
	v_mov_b64_e32 v[124:125], v[4:5]
	v_mov_b64_e32 v[126:127], v[4:5]
	v_mov_b64_e32 v[128:129], v[4:5]
	v_mov_b64_e32 v[130:131], v[4:5]
	v_mov_b64_e32 v[132:133], v[4:5]
	v_mov_b64_e32 v[24:25], v[4:5]
	v_mov_b64_e32 v[56:57], v[4:5]
	v_mov_b64_e32 v[28:29], v[4:5]
	v_mov_b64_e32 v[60:61], v[4:5]
	v_mov_b64_e32 v[36:37], v[4:5]
	v_mov_b64_e32 v[68:69], v[4:5]
	v_mov_b64_e32 v[32:33], v[4:5]
	v_mov_b64_e32 v[64:65], v[4:5]
	v_mov_b64_e32 v[12:13], v[4:5]
	v_mov_b64_e32 v[44:45], v[4:5]
	v_mov_b64_e32 v[16:17], v[4:5]
	v_mov_b64_e32 v[48:49], v[4:5]
	v_mov_b64_e32 v[20:21], v[4:5]
	v_mov_b64_e32 v[52:53], v[4:5]
	v_mov_b64_e32 v[8:9], v[4:5]
	v_mov_b64_e32 v[40:41], v[4:5]
	s_addc_u32 s44, s1, 0
	s_mov_b32 s45, -2
	v_mov_b64_e32 v[22:23], v[2:3]
	v_mov_b64_e32 v[54:55], v[2:3]
	v_mov_b64_e32 v[26:27], v[2:3]
	v_mov_b64_e32 v[58:59], v[2:3]
	v_mov_b64_e32 v[34:35], v[2:3]
	v_mov_b64_e32 v[66:67], v[2:3]
	v_mov_b64_e32 v[30:31], v[2:3]
	v_mov_b64_e32 v[62:63], v[2:3]
	v_mov_b64_e32 v[10:11], v[2:3]
	v_mov_b64_e32 v[42:43], v[2:3]
	v_mov_b64_e32 v[14:15], v[2:3]
	v_mov_b64_e32 v[46:47], v[2:3]
	v_mov_b64_e32 v[18:19], v[2:3]
	v_mov_b64_e32 v[50:51], v[2:3]
	v_mov_b64_e32 v[6:7], v[2:3]
	v_mov_b64_e32 v[38:39], v[2:3]
	s_and_b64 vcc, exec, s[86:87]
	s_cbranch_vccnz .LBB0_107
	s_add_u32 s2, s0, 0x100
	s_addc_u32 s3, s1, 0
	s_add_u32 s84, s76, 0x100
	s_addc_u32 s85, s77, 0
	v_add_u32_e32 v220, 0x18000, v247
	v_add_u32_e32 v221, 0x1c000, v247
	v_add_u32_e32 v222, 0xc000, v247
	v_add_u32_e32 v223, 0x20000, v247
	s_mov_b32 s45, 0
	s_waitcnt vmcnt(0)
	s_and_b64 vcc, exec, s[14:15]
	s_cbranch_vccz .Lhu_y
